# baseline (speedup 1.0000x reference)
; template <int DUMMY>
; __device__ void ssd_item(const Params& p, int item) {
;     ...
;     __builtin_amdgcn_s_setprio(1);
;     {
;       const int sfb = (wid & 1) * 2;
;       f32x4 cb[2];
;       cb[0] = f32x4{0.f, 0.f, 0.f, 0.f};
;       cb[1] = f32x4{0.f, 0.f, 0.f, 0.f};
; #pragma unroll
;       for (int ks = 0; ks < 4; ++ks) {
;         bf16x8 a = *(const bf16x8*)(Cs + (lf * 16 + fr) * 136 + ks * 32 + g4 * 8);
; #pragma unroll
;         for (int j = 0; j < 2; ++j) {
;           bf16x8 bb = *(const bf16x8*)(Bs + ((sfb + j) * 16 + fr) * 136 + ks * 32 + g4 * 8);
;           cb[j] = __builtin_amdgcn_mfma_f32_16x16x32_bf16(a, bb, cb[j], 0, 0, 0);
;         }
;       }
; #pragma unroll
;       for (int j = 0; j < 2; ++j) {
;         int s_ = (sfb + j) * 16 + fr;
;         float cs_s = cs[s_];
; #pragma unroll
;         for (int r = 0; r < 4; ++r) {
;           int l_ = lf * 16 + g4 * 4 + r;
;           float gv = (s_ <= l_) ? cb[j][r] * __expf(cs[l_] - cs_s) : 0.f;
;           Gs[l_ * 72 + s_] = f2bf(gv);
;         }
;       }
;     }
;     {
;       float dec = __expf(cs[63]);
; #pragma unroll
;       for (int j = 0; j < 2; ++j) {
;         accS[j][0] *= dec; accS[j][1] *= dec; accS[j][2] *= dec; accS[j][3] *= dec;
;       }
; #pragma unroll
;       for (int ks = 0; ks < 2; ++ks) {
;         bf16x8 a = *(const bf16x8*)(xwT + (pf * 16 + fr) * 72 + ks * 32 + g4 * 8);
; #pragma unroll
;         for (int j = 0; j < 2; ++j) {
;           bf16x8 bb = *(const bf16x8*)(BTs + ((nf0 + j) * 16 + fr) * 72 + ks * 32 + g4 * 8);
;           accS[j] = __builtin_amdgcn_mfma_f32_16x16x32_bf16(a, bb, accS[j], 0, 0, 0);
;         }
;       }
;     }
;     __builtin_amdgcn_s_setprio(0);
.LBB0_1051:
	s_or_b64 exec, exec, s[30:31]
	s_setprio 1
	v_add3_u32 v42, s3, v158, v161
	ds_read_b128 v[32:35], v42
	ds_read_b128 v[36:39], v154 offset:17408
	ds_read_b128 v[178:181], v154 offset:21760
	ds_read_b128 v[182:185], v42 offset:64
	ds_read_b128 v[186:189], v154 offset:17472
	ds_read_b128 v[220:223], v154 offset:21824
	ds_read_b128 v[224:227], v42 offset:128
	ds_read_b128 v[228:231], v154 offset:17536
	v_lshl_add_u32 v100, v121, 2, s52
	v_mov_b32_e32 v177, 0
	v_lshl_add_u32 v87, v119, 2, s52
	s_waitcnt lgkmcnt(6)
	v_mfma_f32_16x16x32_bf16 v[36:39], v[32:35], v[36:39], 0
	s_waitcnt lgkmcnt(5)
	v_mfma_f32_16x16x32_bf16 v[32:35], v[32:35], v[178:181], 0
	ds_read_b128 v[232:235], v154 offset:21888
	ds_read_b128 v[236:239], v42 offset:192
	ds_read_b128 v[240:243], v154 offset:17600
	ds_read_b128 v[244:247], v154 offset:21952
	ds_read_b32 v216, v87
	ds_read_b32 v217, v87 offset:4
	ds_read_b32 v218, v87 offset:8
	ds_read_b32 v219, v87 offset:12
	ds_read_b32 v101, v100
	ds_read_b32 v252, v100 offset:64
	s_waitcnt lgkmcnt(13)
	v_mfma_f32_16x16x32_bf16 v[36:39], v[182:185], v[186:189], v[36:39]
	s_waitcnt lgkmcnt(12)
	v_mfma_f32_16x16x32_bf16 v[32:35], v[182:185], v[220:223], v[32:35]
	s_waitcnt lgkmcnt(10)
	v_mfma_f32_16x16x32_bf16 v[36:39], v[224:227], v[228:231], v[36:39]
	s_waitcnt lgkmcnt(9)
	v_mfma_f32_16x16x32_bf16 v[32:35], v[224:227], v[232:235], v[32:35]
	s_waitcnt lgkmcnt(7)
	v_mfma_f32_16x16x32_bf16 v[36:39], v[236:239], v[240:243], v[36:39]
	s_waitcnt lgkmcnt(6)
	v_mfma_f32_16x16x32_bf16 v[32:35], v[236:239], v[244:247], v[32:35]
	s_waitcnt lgkmcnt(0)
	v_mov_b32_e32 v228, v252
	v_sub_f32_e32 v220, v216, v101
	v_sub_f32_e32 v221, v217, v101
	v_sub_f32_e32 v222, v218, v101
	v_sub_f32_e32 v223, v219, v101
	v_sub_f32_e32 v224, v216, v228
	v_sub_f32_e32 v225, v217, v228
	v_sub_f32_e32 v226, v218, v228
	v_sub_f32_e32 v227, v219, v228
	v_mul_f32_e32 v220, 0x3fb8aa3b, v220
	v_mul_f32_e32 v221, 0x3fb8aa3b, v221
	v_mul_f32_e32 v222, 0x3fb8aa3b, v222
	v_mul_f32_e32 v223, 0x3fb8aa3b, v223
	v_mul_f32_e32 v224, 0x3fb8aa3b, v224
	v_mul_f32_e32 v225, 0x3fb8aa3b, v225
	v_mul_f32_e32 v226, 0x3fb8aa3b, v226
	v_mul_f32_e32 v227, 0x3fb8aa3b, v227
	v_exp_f32_e32 v220, v220
	v_exp_f32_e32 v221, v221
	v_exp_f32_e32 v222, v222
	v_exp_f32_e32 v223, v223
	v_exp_f32_e32 v224, v224
	v_exp_f32_e32 v225, v225
	v_exp_f32_e32 v226, v226
	v_exp_f32_e32 v227, v227
	v_mul_f32_e32 v220, v36, v220
	v_mul_f32_e32 v221, v37, v221
	v_mul_f32_e32 v222, v38, v222
	v_mul_f32_e32 v223, v39, v223
	v_mul_f32_e32 v224, v32, v224
	v_mul_f32_e32 v225, v33, v225
	v_mul_f32_e32 v226, v34, v226
	v_mul_f32_e32 v227, v35, v227
	v_cvt_pk_bf16_f32 v220, v220, s0
	v_cvt_pk_bf16_f32 v221, v221, s0
	v_cvt_pk_bf16_f32 v222, v222, s0
	v_cvt_pk_bf16_f32 v223, v223, s0
	v_cvt_pk_bf16_f32 v224, v224, s0
	v_cvt_pk_bf16_f32 v225, v225, s0
	v_cvt_pk_bf16_f32 v226, v226, s0
	v_cvt_pk_bf16_f32 v227, v227, s0
	v_cndmask_b32_e64 v220, 0, v220, s[6:7]
	v_cndmask_b32_e64 v221, 0, v221, s[8:9]
	v_cndmask_b32_e64 v222, 0, v222, s[10:11]
	v_cndmask_b32_e64 v223, 0, v223, s[12:13]
	v_cndmask_b32_e64 v224, 0, v224, s[14:15]
	v_cndmask_b32_e64 v225, 0, v225, s[16:17]
	v_cndmask_b32_e64 v226, 0, v226, s[18:19]
	v_cndmask_b32_e64 v227, 0, v227, s[20:21]
	ds_write_b16 v124, v220
	ds_write_b16 v125, v221
	ds_write_b16 v126, v222
	ds_write_b16 v127, v223
	ds_write_b16 v128, v224
	ds_write_b16 v129, v225
	ds_write_b16 v130, v226
	v_mov_b32_e32 v32, v227
	v_mov_b32_e32 v33, s52
	ds_read_b32 v100, v33 offset:252
	ds_write_b16 v131, v32
	ds_read_b128 v[32:35], v134 offset:57856
	s_waitcnt lgkmcnt(7)
	ds_read_b128 v[36:39], v136 offset:34816
	ds_read_b128 v[178:181], v138 offset:34816
	ds_read_b128 v[182:185], v134 offset:57920
	ds_read_b128 v[186:189], v136 offset:34880
	s_waitcnt lgkmcnt(6)
	v_mul_f32_e32 v100, 0x3fb8aa3b, v100
	v_exp_f32_e32 v100, v100
	s_nop 0
	v_pk_mul_f32 v[6:7], v[6:7], v[100:101] op_sel_hi:[1,0]
	v_pk_mul_f32 v[4:5], v[4:5], v[100:101] op_sel_hi:[1,0]
	v_pk_mul_f32 v[2:3], v[2:3], v[100:101] op_sel_hi:[1,0]
	v_pk_mul_f32 v[0:1], v[0:1], v[100:101] op_sel_hi:[1,0]
	s_waitcnt lgkmcnt(3)
	v_mfma_f32_16x16x32_bf16 v[4:7], v[32:35], v[36:39], v[4:7]
	ds_read_b128 v[36:39], v138 offset:34880
	s_waitcnt lgkmcnt(3)
	v_mfma_f32_16x16x32_bf16 v[0:3], v[32:35], v[178:181], v[0:3]
	s_waitcnt lgkmcnt(1)
	v_mfma_f32_16x16x32_bf16 v[4:7], v[182:185], v[186:189], v[4:7]
	s_waitcnt lgkmcnt(0)
	v_mfma_f32_16x16x32_bf16 v[0:3], v[182:185], v[36:39], v[0:3]
	s_setprio 0
	s_waitcnt lgkmcnt(0)
	s_barrier
; __device__ __forceinline__ float bf2f(u16 h) { return __uint_as_float(((unsigned)h) << 16); }
; __device__ __forceinline__ float siluf_(float v) { return v * __builtin_amdgcn_rcpf(1.f + __expf(-v)); }
; template <int DUMMY>
; __device__ void ssd_item(const Params& p, int item) {
;     ...
;     __builtin_amdgcn_s_setprio(1);
;     {
;       f32x4 yd = {0.f, 0.f, 0.f, 0.f}, yo = {0.f, 0.f, 0.f, 0.f};
; #pragma unroll
;       for (int ks = 0; ks < 2; ++ks) {
;         bf16x8 a = *(const bf16x8*)(Gs + (lf * 16 + fr) * 72 + ks * 32 + g4 * 8);
;         bf16x8 bb = *(const bf16x8*)(xdT + (pf * 16 + fr) * 72 + ks * 32 + g4 * 8);
;         yd = __builtin_amdgcn_mfma_f32_16x16x32_bf16(a, bb, yd, 0, 0, 0);
;       }
; #pragma unroll
;       for (int ks = 0; ks < 4; ++ks) {
;         bf16x8 a = *(const bf16x8*)(Cs + (lf * 16 + fr) * 136 + ks * 32 + g4 * 8);
;         bf16x8 bb = *(const bf16x8*)(Sb + (pf * 16 + fr) * 136 + ks * 32 + g4 * 8);
;         yo = __builtin_amdgcn_mfma_f32_16x16x32_bf16(a, bb, yo, 0, 0, 0);
;       }
;       __builtin_amdgcn_s_setprio(0);
;       bf16x4 xs4 = *(const bf16x4*)(xT + (pf * 16 + fr) * 72 + lf * 16 + g4 * 4);
; #pragma unroll
;       for (int r = 0; r < 4; ++r) {
;         int l_ = lf * 16 + g4 * 4 + r;
;         float y = yd[r] + __expf(cs[l_]) * yo[r] + Dh * bf2f((u16)xs4[r]);
;         y *= siluf_(bf2f(zcur[r]));
;         ytile[l_ * 36 + pf * 16 + fr] = f2bf(y);
;         float sq = row16_sum(y * y);
;         if (fr == 0) sqs[wid * 16 + g4 * 4 + r] = sq;
;       }
;       zbase += (size_t)64 * 4096;
;     }
;     cur3 = nxt3;
	s_setprio 1
	ds_read_b128 v[32:35], v42
	v_add3_u32 v100, s78, v162, v161
	ds_read_b128 v[36:39], v100
	ds_read_b128 v[178:181], v132
	ds_read_b128 v[182:185], v42 offset:64
	ds_read_b128 v[186:189], v100 offset:64
	v_add3_u32 v101, s53, v160, v161
	s_waitcnt lgkmcnt(3)
	v_mfma_f32_16x16x32_bf16 v[32:35], v[32:35], v[36:39], 0
	ds_read_b128 v[36:39], v101
	ds_read_b128 v[190:193], v132 offset:64
	ds_read_b128 v[194:197], v101 offset:64
	s_waitcnt lgkmcnt(2)
	v_mfma_f32_16x16x32_bf16 v[178:181], v[178:181], v[36:39], 0
	ds_read_b128 v[36:39], v42 offset:128
	ds_read_b128 v[198:201], v42 offset:192
	v_mfma_f32_16x16x32_bf16 v[32:35], v[182:185], v[186:189], v[32:35]
	ds_read_b128 v[182:185], v100 offset:128
	ds_read_b128 v[186:189], v100 offset:192
	s_waitcnt lgkmcnt(1)
	v_mfma_f32_16x16x32_bf16 v[32:35], v[36:39], v[182:185], v[32:35]
	s_waitcnt lgkmcnt(0)
	v_mfma_f32_16x16x32_bf16 v[36:39], v[198:201], v[186:189], v[32:35]
	v_mfma_f32_16x16x32_bf16 v[32:35], v[190:193], v[194:197], v[178:181]
	s_setprio 0
	v_add_u32_e32 v42, s77, v160
	v_add3_u32 v42, v42, v163, v164
	ds_read_b64 v[100:101], v42
	v_lshlrev_b32_e32 v220, 16, v167
	v_lshlrev_b32_e32 v221, 16, v166
	v_lshlrev_b32_e32 v222, 16, v165
	v_lshlrev_b32_e32 v223, 16, v75
	v_mul_f32_e32 v224, 0xbfb8aa3b, v220
	v_mul_f32_e32 v225, 0xbfb8aa3b, v221
	v_mul_f32_e32 v226, 0xbfb8aa3b, v222
	v_mul_f32_e32 v227, 0xbfb8aa3b, v223
	v_mul_f32_e32 v228, 0x3fb8aa3b, v216
	v_mul_f32_e32 v229, 0x3fb8aa3b, v217
	v_mul_f32_e32 v230, 0x3fb8aa3b, v218
	v_mul_f32_e32 v231, 0x3fb8aa3b, v219
	v_exp_f32_e32 v224, v224
	v_exp_f32_e32 v225, v225
	v_exp_f32_e32 v226, v226
	v_exp_f32_e32 v227, v227
	v_exp_f32_e32 v228, v228
	v_exp_f32_e32 v229, v229
	v_exp_f32_e32 v230, v230
	v_exp_f32_e32 v231, v231
	v_add_f32_e32 v224, 1.0, v224
	v_add_f32_e32 v225, 1.0, v225
	v_add_f32_e32 v226, 1.0, v226
	v_add_f32_e32 v227, 1.0, v227
	v_rcp_f32_e32 v224, v224
	v_rcp_f32_e32 v225, v225
	v_rcp_f32_e32 v226, v226
	v_rcp_f32_e32 v227, v227
	v_fma_f32 v32, v36, v228, v32
	v_fma_f32 v33, v37, v229, v33
	v_fma_f32 v34, v38, v230, v34
	v_fmac_f32_e32 v35, v39, v231
	s_waitcnt lgkmcnt(0)
	v_lshlrev_b32_e32 v232, 16, v100
	v_and_b32_e32 v233, 0xffff0000, v100
	v_lshlrev_b32_e32 v234, 16, v101
	v_and_b32_e32 v235, 0xffff0000, v101
	v_fmac_f32_e32 v32, v43, v232
	v_mul_f32_e32 v233, v43, v233
	v_mul_f32_e32 v234, v43, v234
	v_mul_f32_e32 v235, v43, v235
	v_add_f32_e32 v33, v233, v33
	v_add_f32_e32 v34, v234, v34
	v_add_f32_e32 v35, v235, v35
	v_mul_f32_e32 v224, v224, v220
	v_mul_f32_e32 v225, v225, v221
	v_mul_f32_e32 v226, v226, v222
	v_mul_f32_e32 v227, v227, v223
	v_mul_f32_e32 v32, v224, v32
	v_mul_f32_e32 v33, v225, v33
	v_mul_f32_e32 v34, v226, v34
	v_mul_f32_e32 v35, v227, v35
	v_cvt_pk_bf16_f32 v228, v32, s0
	v_cvt_pk_bf16_f32 v229, v33, s0
	v_cvt_pk_bf16_f32 v230, v34, s0
	v_cvt_pk_bf16_f32 v231, v35, s0
	ds_write_b16 v123, v228
	ds_write_b16 v123, v229 offset:72
	ds_write_b16 v123, v230 offset:144
	ds_write_b16 v123, v231 offset:216
	v_mul_f32_e32 v236, v32, v32
	v_mul_f32_e32 v237, v33, v33
	v_mul_f32_e32 v238, v34, v34
	v_mul_f32_e32 v239, v35, v35
	v_mov_b32_dpp v240, v236 quad_perm:[1,0,3,2] row_mask:0xf bank_mask:0xf bound_ctrl:1
	v_mov_b32_dpp v241, v237 quad_perm:[1,0,3,2] row_mask:0xf bank_mask:0xf bound_ctrl:1
	v_mov_b32_dpp v242, v238 quad_perm:[1,0,3,2] row_mask:0xf bank_mask:0xf bound_ctrl:1
	v_mov_b32_dpp v243, v239 quad_perm:[1,0,3,2] row_mask:0xf bank_mask:0xf bound_ctrl:1
	v_fmac_f32_e32 v240, v32, v32
	v_fmac_f32_e32 v241, v33, v33
	v_fmac_f32_e32 v242, v34, v34
	v_fmac_f32_e32 v243, v35, v35
	v_add_f32_dpp v236, v240, v240 quad_perm:[2,3,0,1] row_mask:0xf bank_mask:0xf bound_ctrl:1
	v_add_f32_dpp v237, v241, v241 quad_perm:[2,3,0,1] row_mask:0xf bank_mask:0xf bound_ctrl:1
	v_add_f32_dpp v238, v242, v242 quad_perm:[2,3,0,1] row_mask:0xf bank_mask:0xf bound_ctrl:1
	v_add_f32_dpp v239, v243, v243 quad_perm:[2,3,0,1] row_mask:0xf bank_mask:0xf bound_ctrl:1
	v_add_f32_dpp v236, v236, v236 row_half_mirror row_mask:0xf bank_mask:0xf bound_ctrl:1
	v_add_f32_dpp v237, v237, v237 row_half_mirror row_mask:0xf bank_mask:0xf bound_ctrl:1
	v_add_f32_dpp v238, v238, v238 row_half_mirror row_mask:0xf bank_mask:0xf bound_ctrl:1
	v_add_f32_dpp v239, v239, v239 row_half_mirror row_mask:0xf bank_mask:0xf bound_ctrl:1
	v_mov_b32_dpp v240, v236 row_mirror row_mask:0xf bank_mask:0xf bound_ctrl:1
	v_mov_b32_dpp v241, v237 row_mirror row_mask:0xf bank_mask:0xf bound_ctrl:1
	v_mov_b32_dpp v242, v238 row_mirror row_mask:0xf bank_mask:0xf bound_ctrl:1
	v_mov_b32_dpp v243, v239 row_mirror row_mask:0xf bank_mask:0xf bound_ctrl:1
	s_and_saveexec_b64 s[30:31], s[0:1]
	v_add_f32_e32 v236, v236, v240
	v_add_f32_e32 v237, v237, v241
	v_add_f32_e32 v238, v238, v242
	v_add_f32_e32 v239, v239, v243
	ds_write_b32 v122, v236
	ds_write_b32 v122, v237 offset:4
	ds_write_b32 v122, v238 offset:8
	ds_write_b32 v122, v239 offset:12
	s_or_b64 exec, exec, s[30:31]
	s_add_u32 s70, s70, 0x40000
	s_addc_u32 s71, s71, 0
	s_mov_b64 s[30:31], 0x4000
	s_add_i32 s76, s76, 1
	s_waitcnt vmcnt(4)
	v_perm_b32 v42, v40, v176, s94
	v_perm_b32 v100, v176, v175, s94
	v_perm_b32 v101, v175, v173, s94
	v_perm_b32 v173, v173, v174, s94
	v_perm_b32 v171, v172, v171, s94
	v_lshl_add_u64 v[84:85], v[84:85], 0, s[60:61]
	v_add_u32_e32 v86, 64, v86
	v_lshl_add_u64 v[92:93], v[92:93], 0, s[30:31]
	v_lshl_add_u64 v[94:95], v[94:95], 0, s[62:63]
	v_lshl_add_u64 v[96:97], v[96:97], 0, s[62:63]
	s_cmp_eq_u32 s70, 0x1f00000
	v_lshl_add_u64 v[98:99], v[98:99], 0, s[60:61]
	s_waitcnt vmcnt(0)
	v_mov_b32_e32 v118, v255
	s_cbranch_scc1 .LBB0_1077
; template <int DUMMY>
; __device__ void ssd_item(const Params& p, int item) {
;     ...
;     for (int r = 0; r < 4; ++r) zcur[r] = znext[r];
;     if (c > 1) {
;       const size_t yi = (tb + (c - 2) * 64 + (tid >> 3)) * 4096 + h * 64 + ph * 32 + (tid & 7) * 4;
;       *(i32x2*)(zyo + (yi & omask)) = ypend;
;     }
;     if (c + 1 < 128) {
;       load_raw(c + 1);
;       const size_t zn = zbase + (size_t)64 * 4096;
; #pragma unroll
;       for (int r = 0; r < 4; ++r) znext[r] = zy[zn + (size_t)r * 4096];
	s_waitcnt vmcnt(0)
	v_mov_b32_e32 v75, v49
	v_mov_b32_e32 v165, v168
	v_mov_b32_e32 v166, v169
	v_mov_b32_e32 v167, v170
	v_lshl_add_u64 v[224:225], v[78:79], 0, s[70:71]
	v_lshl_add_u64 v[226:227], v[80:81], 0, s[70:71]
	v_add_co_u32_e32 v224, vcc, 0x100000, v224
	s_nop 1
	v_addc_co_u32_e32 v225, vcc, 0, v225, vcc
	v_add_co_u32_e32 v226, vcc, 0x100000, v226
	s_nop 1
	v_addc_co_u32_e32 v227, vcc, 0, v227, vcc
	global_load_dword v253, v[224:225], off
	global_load_dword v253, v[224:225], off offset:2048
	global_load_dword v253, v[226:227], off
	global_load_dword v253, v[226:227], off offset:2048
	v_add_u32_e32 v224, 61, v86
	v_mov_b32_e32 v225, v41
	v_lshl_add_u64 v[224:225], s[64:65], 0, v[224:225]
	v_mad_u64_u32 v[226:227], s[72:73], v224, s86, v[66:67]
	v_mad_i32_i24 v227, v225, s86, v227
	global_load_ushort v253, v[226:227], off
	v_add_co_u32_e32 v226, vcc, 0x3000, v226
	s_nop 1
	v_addc_co_u32_e32 v227, vcc, 0, v227, vcc
	global_load_ushort v253, v[226:227], off
	v_add_co_u32_e32 v226, vcc, 0x3000, v226
	s_nop 1
	v_addc_co_u32_e32 v227, vcc, 0, v227, vcc
	global_load_ushort v253, v[226:227], off
	v_add_co_u32_e32 v226, vcc, 0x3000, v226
	s_nop 1
	v_addc_co_u32_e32 v227, vcc, 0, v227, vcc
	global_load_ushort v253, v[226:227], off
	v_lshl_add_u64 v[224:225], v[84:85], 0, s[60:61]
	v_lshl_add_u64 v[224:225], s[42:43], 0, v[224:225]
	v_add_co_u32_e32 v226, vcc, 0xb280000, v224
	s_nop 1
	v_addc_co_u32_e32 v227, vcc, 0, v225, vcc
	global_load_ushort v253, v[226:227], off
	v_add_co_u32_e32 v226, vcc, 0xb282000, v224
	s_nop 1
	v_addc_co_u32_e32 v227, vcc, 0, v225, vcc
	global_load_ushort v253, v[226:227], off
	v_add_co_u32_e32 v226, vcc, 0xb284000, v224
	s_nop 1
	v_addc_co_u32_e32 v227, vcc, 0, v225, vcc
	global_load_ushort v253, v[226:227], off
	v_add_co_u32_e32 v226, vcc, 0xb286000, v224
	s_nop 1
	v_addc_co_u32_e32 v227, vcc, 0, v225, vcc
	global_load_ushort v253, v[226:227], off
	s_branch .LBB0_1033
